# scan: staging waves yield longer (s_sleep 10) after the chunk barrier
# baseline (speedup 1.0000x reference)
; #define UFOR(v, n) _Pragma("unroll") for (int v = 0; v < (n); ++v)
; __device__ __forceinline__ float h2f(u16 u) { _Float16 h = __builtin_bit_cast(_Float16, u); return (float)h; }
; __device__ __forceinline__ void phase_scan(KP p) {
;     ...
;       if (w >= 4) {
;         if (((c + 1) & 1) == ppair) {
;           if (c + 1 < NCH) {
;             const int buf = (c + 1) & 1;
;             UFOR(e, 2) {
;               const int q = pt + 128 * e, st = q >> 3, g8 = q & 7;
;               float f[8];
;               float* fd = feat + ((buf * 32 + st) * 5) * 64 + g8 * 8;
;               unpack8(rq[e][0], f); *(float4*)(fd) = make_float4(f[0], f[1], f[2], f[3]); *(float4*)(fd + 4) = make_float4(f[4], f[5], f[6], f[7]);
;               { const uint4 u = rq[e][1];
;                 f[0] = h2f((u16)(u.x & 0xffff)); f[1] = h2f((u16)(u.x >> 16)); f[2] = h2f((u16)(u.y & 0xffff)); f[3] = h2f((u16)(u.y >> 16));
;                 f[4] = h2f((u16)(u.z & 0xffff)); f[5] = h2f((u16)(u.z >> 16)); f[6] = h2f((u16)(u.w & 0xffff)); f[7] = h2f((u16)(u.w >> 16));
;                 UFOR(x, 8) f[x] = __expf(-f[x]);
;                 *(float4*)(fd + 64) = make_float4(f[0], f[1], f[2], f[3]); *(float4*)(fd + 68) = make_float4(f[4], f[5], f[6], f[7]); }
;               unpack8(rq[e][2], f); *(float4*)(fd + 128) = make_float4(f[0], f[1], f[2], f[3]); *(float4*)(fd + 132) = make_float4(f[4], f[5], f[6], f[7]);
;               unpack8(rq[e][3], f); *(float4*)(fd + 192) = make_float4(-f[0], -f[1], -f[2], -f[3]); *(float4*)(fd + 196) = make_float4(-f[4], -f[5], -f[6], -f[7]);
;               unpack8(rq[e][4], f); *(float4*)(fd + 256) = make_float4(f[0], f[1], f[2], f[3]); *(float4*)(fd + 260) = make_float4(f[4], f[5], f[6], f[7]);
;               if ((g8 >> 1) == rg) {
;                 unpack8(rq[e][5], f);
;                 float* vd = vbuf + (buf * 16 + (g8 & 1) * 8) * 32 + st;
;                 UFOR(x, 8) vd[x * 32] = f[x];
;               }
.LBB0_756:
	s_and_saveexec_b64 s[50:51], vcc
	s_xor_b64 s[70:71], exec, s[50:51]
	s_cbranch_execz .LBB0_770
	s_sleep 10
	v_xor_b32_e32 v48, s18, v111
	v_and_b32_e32 v48, 1, v48
	v_cmp_eq_u32_e64 s[50:51], 1, v48
	s_and_saveexec_b64 s[72:73], s[50:51]
	s_xor_b64 s[72:73], exec, s[72:73]
	s_cbranch_execz .LBB0_766
	s_cmpk_eq_i32 s18, 0x207
	s_cbranch_scc1 .LBB0_764
	s_waitcnt vmcnt(0)
	v_and_b32_e32 v56, 7, v135
	v_bfe_u32 v57, v135, 3, 4
	v_bfe_u32 v58, v135, 7, 1
	v_lshl_add_u32 v57, v58, 5, v57
	v_mul_u32_u24_e32 v57, 0x220, v57
	v_lshrrev_b32_e32 v58, 2, v56
	v_and_b32_e32 v56, 3, v56
	v_lshlrev_b32_e32 v58, 4, v58
	v_lshl_add_u32 v56, v56, 2, v58
	s_mov_b32 s74, 0x16000
	v_add3_u32 v64, v57, v56, s74
	v_add_u32_e32 v65, 0x2200, v64
	s_mov_b32 s74, 0x5040100
	s_mov_b32 s75, 0x7060302
	v_perm_b32 v60, v6, v4, s74
	v_perm_b32 v61, v6, v4, s75
	v_perm_b32 v62, v7, v5, s74
	v_perm_b32 v63, v7, v5, s75
	ds_write2_b32 v64, v60, v61 offset0:0 offset1:8
	ds_write2_b32 v64, v62, v63 offset0:16 offset1:24
	v_perm_b32 v60, v10, v8, s74
	v_perm_b32 v61, v10, v8, s75
	v_perm_b32 v62, v11, v9, s74
	v_perm_b32 v63, v11, v9, s75
	ds_write2_b32 v64, v60, v61 offset0:32 offset1:40
	ds_write2_b32 v64, v62, v63 offset0:48 offset1:56
	v_perm_b32 v60, v14, v12, s74
	v_perm_b32 v61, v14, v12, s75
	v_perm_b32 v62, v15, v13, s74
	v_perm_b32 v63, v15, v13, s75
	v_xor_b32_e32 v60, 0x80008000, v60
	v_xor_b32_e32 v61, 0x80008000, v61
	v_xor_b32_e32 v62, 0x80008000, v62
	v_xor_b32_e32 v63, 0x80008000, v63
	ds_write2_b32 v64, v60, v61 offset0:64 offset1:72
	ds_write2_b32 v64, v62, v63 offset0:80 offset1:88
	v_perm_b32 v60, v18, v16, s74
	v_perm_b32 v61, v18, v16, s75
	v_perm_b32 v62, v19, v17, s74
	v_perm_b32 v63, v19, v17, s75
	ds_write2_b32 v64, v60, v61 offset0:96 offset1:104
	ds_write2_b32 v64, v62, v63 offset0:112 offset1:120
	v_cvt_f32_f16_e32 v48, v0
	v_cvt_f32_f16_sdwa v49, v0 dst_sel:DWORD dst_unused:UNUSED_PAD src0_sel:WORD_1
	v_cvt_f32_f16_e32 v50, v1
	v_cvt_f32_f16_sdwa v51, v1 dst_sel:DWORD dst_unused:UNUSED_PAD src0_sel:WORD_1
	v_cvt_f32_f16_e32 v52, v2
	v_cvt_f32_f16_sdwa v53, v2 dst_sel:DWORD dst_unused:UNUSED_PAD src0_sel:WORD_1
	v_cvt_f32_f16_e32 v54, v3
	v_cvt_f32_f16_sdwa v55, v3 dst_sel:DWORD dst_unused:UNUSED_PAD src0_sel:WORD_1
	v_mul_f32_e32 v48, 0xbfb8aa3b, v48
	v_mul_f32_e32 v49, 0xbfb8aa3b, v49
	v_mul_f32_e32 v50, 0xbfb8aa3b, v50
	v_mul_f32_e32 v51, 0xbfb8aa3b, v51
	v_exp_f32_e32 v48, v48
	v_exp_f32_e32 v49, v49
	v_exp_f32_e32 v50, v50
	v_exp_f32_e32 v51, v51
	v_mul_f32_e32 v52, 0xbfb8aa3b, v52
	v_mul_f32_e32 v53, 0xbfb8aa3b, v53
	v_mul_f32_e32 v54, 0xbfb8aa3b, v54
	v_mul_f32_e32 v55, 0xbfb8aa3b, v55
	v_exp_f32_e32 v52, v52
	v_exp_f32_e32 v53, v53
	v_exp_f32_e32 v54, v54
	v_exp_f32_e32 v55, v55
	ds_write_b128 v149, v[48:51] offset:256
	ds_write_b128 v149, v[52:55] offset:272
	s_and_saveexec_b64 s[50:51], s[48:49]
	s_cbranch_execz .LBB0_761
	v_lshlrev_b32_e32 v48, 16, v20
	v_and_b32_e32 v49, 0xffff0000, v20
	v_lshlrev_b32_e32 v50, 16, v21
	v_and_b32_e32 v51, 0xffff0000, v21
	v_lshlrev_b32_e32 v52, 16, v22
	v_and_b32_e32 v53, 0xffff0000, v22
	v_lshlrev_b32_e32 v54, 16, v23
	v_and_b32_e32 v55, 0xffff0000, v23
	ds_write2_b32 v130, v48, v49 offset1:32
	ds_write2_b32 v130, v50, v51 offset0:64 offset1:96
	ds_write2_b32 v130, v52, v53 offset0:128 offset1:160
	ds_write2_b32 v130, v54, v55 offset0:192 offset1:224
